# xattn: second half of the next unit's K tile prefetched during PV
# speedup vs baseline: 1.0087x; 1.0087x over previous
.LBB0_1947:
	v_readlane_b32 s4, v244, 47
	s_cmp_lt_i32 s4, 10
	s_cselect_b64 s[2:3], -1, 0
	s_and_b64 s[2:3], s[2:3], s[0:1]
	s_cmpk_lt_i32 s69, 0x600
	s_cselect_b64 s[0:1], -1, 0
	s_and_b64 s[0:1], s[2:3], s[0:1]
	s_andn2_b64 vcc, exec, s[0:1]
	v_readlane_b32 s5, v244, 48
	v_readlane_b32 s6, v244, 49
	v_readlane_b32 s7, v244, 50
	s_cbranch_vccnz .LBB0_1956
	v_and_b32_e32 v249, 63, v182
	v_readlane_b32 s4, v244, 6
	v_readlane_b32 s5, v244, 7
	v_readlane_b32 s6, v244, 39
	v_readlane_b32 s7, v244, 40
	v_readlane_b32 s8, v244, 41
	v_readlane_b32 s9, v244, 42
	v_lshlrev_b32_e32 v242, 2, v249
	s_nop 3
	global_load_dword v216, v242, s[6:7] offset:0
	global_load_dword v217, v242, s[6:7] offset:256
	global_load_dword v218, v242, s[6:7] offset:512
	global_load_dword v219, v242, s[6:7] offset:768
	global_load_dword v220, v242, s[8:9] offset:0
	global_load_dword v221, v242, s[8:9] offset:256
	global_load_dword v222, v242, s[8:9] offset:512
	global_load_dword v223, v242, s[8:9] offset:768
	v_and_b32_e32 v243, 15, v182
	v_bfe_u32 v245, v182, 4, 2
	v_lshl_or_b32 v246, s88, 4, v243
	v_lshlrev_b32_e32 v228, 11, v246
	v_lshl_add_u32 v238, v245, 3, v228
	v_lshl_add_u32 v228, v245, 4, v228
	v_add_u32_e32 v229, 0x40000, v228
	v_add_u32_e32 v239, 0x40000, v238
	v_lshlrev_b32_e32 v230, 4, v246
	v_mul_u32_u24_e32 v231, 528, v243
	v_lshl_add_u32 v232, v245, 3, v231
	v_lshl_add_u32 v231, v245, 4, v231
	v_lshrrev_b32_e32 v243, 5, v182
	v_and_b32_e32 v245, 31, v182
	v_lshlrev_b32_e32 v245, 4, v245
	v_lshl_add_u32 v224, v243, 11, v245
	v_mul_u32_u24_e32 v225, 5120, v243
	v_add_u32_e32 v225, v225, v245
	v_mul_u32_u24_e32 v226, 528, v243
	v_add_u32_e32 v226, v226, v245
	v_add_u32_e32 v227, 67584, v226
	v_and_b32_e32 v250, 3, v243
	v_bfe_u32 v242, v243, 2, 1
	v_lshl_or_b32 v250, v242, 4, v250
	v_bfe_u32 v242, v243, 3, 1
	v_lshl_or_b32 v250, v242, 2, v250
	v_mul_u32_u24_e32 v250, 528, v250
	v_add_u32_e32 v250, v250, v245
	v_add_u32_e32 v251, 67584, v250
	v_xor_b32_e32 v236, 16, v249
	v_lshlrev_b32_e32 v236, 2, v236
	v_xor_b32_e32 v237, 32, v249
	v_lshlrev_b32_e32 v237, 2, v237
	v_mov_b32_e32 v181, 0x358637bd
	s_waitcnt vmcnt(0)
	v_mul_f32_e32 v216, v216, v220
	v_mul_f32_e32 v217, v217, v221
	v_mul_f32_e32 v218, v218, v222
	v_mul_f32_e32 v219, v219, v223
	v_max_f32_e64 v216, |v216|, |v217|
	v_max_f32_e64 v218, |v218|, |v219|
	v_max_f32_e32 v216, v216, v218
	v_xor_b32_e32 v242, 1, v249
	v_lshlrev_b32_e32 v242, 2, v242
	ds_bpermute_b32 v243, v242, v216
	s_waitcnt lgkmcnt(0)
	v_max_f32_e32 v216, v216, v243
	v_xor_b32_e32 v242, 2, v249
	v_lshlrev_b32_e32 v242, 2, v242
	ds_bpermute_b32 v243, v242, v216
	s_waitcnt lgkmcnt(0)
	v_max_f32_e32 v216, v216, v243
	v_xor_b32_e32 v242, 4, v249
	v_lshlrev_b32_e32 v242, 2, v242
	ds_bpermute_b32 v243, v242, v216
	s_waitcnt lgkmcnt(0)
	v_max_f32_e32 v216, v216, v243
	v_xor_b32_e32 v242, 8, v249
	v_lshlrev_b32_e32 v242, 2, v242
	ds_bpermute_b32 v243, v242, v216
	s_waitcnt lgkmcnt(0)
	v_max_f32_e32 v216, v216, v243
	v_xor_b32_e32 v242, 16, v249
	v_lshlrev_b32_e32 v242, 2, v242
	ds_bpermute_b32 v243, v242, v216
	s_waitcnt lgkmcnt(0)
	v_max_f32_e32 v216, v216, v243
	v_xor_b32_e32 v242, 32, v249
	v_lshlrev_b32_e32 v242, 2, v242
	ds_bpermute_b32 v243, v242, v216
	s_waitcnt lgkmcnt(0)
	v_max_f32_e32 v216, v216, v243
	v_mul_f32_e32 v180, 0x41b8aa3b, v216
	s_and_b32 s0, s69, 31
	s_lshr_b32 s1, s69, 8
	s_lshl_b32 s1, s1, 5
	s_add_i32 s1, s1, s0
	s_mul_i32 s0, s1, 2731
	s_lshr_b32 s0, s0, 16
	s_mul_i32 s17, s0, 24
	s_sub_i32 s1, s1, s17
	s_bfe_u32 s17, s69, 0x30005
	s_mul_i32 s17, s17, 24
	s_add_i32 s1, s1, s17
	s_lshl_b32 s11, s1, 19
	s_lshl_b32 s12, s0, 9
	s_add_u32 s11, s11, s12
	s_add_u32 s12, s11, 0xf000000
	s_add_u32 s10, s4, s12
	s_addc_u32 s11, s5, 0
	s_lshl_b32 s12, s1, 12
	s_lshl_b32 s13, s0, 2
	s_add_u32 s12, s12, s13
	s_add_u32 s12, s12, 0x1fa60000
	s_add_u32 s12, s4, s12
	s_addc_u32 s13, s5, 0
	global_load_dwordx4 v[0:3], v228, s[10:11] offset:0
	global_load_dwordx4 v[4:7], v228, s[10:11] offset:64
	global_load_dwordx4 v[8:11], v228, s[10:11] offset:128
	global_load_dwordx4 v[12:15], v228, s[10:11] offset:192
	global_load_dwordx4 v[16:19], v228, s[10:11] offset:256
	global_load_dwordx4 v[20:23], v228, s[10:11] offset:320
	global_load_dwordx4 v[24:27], v228, s[10:11] offset:384
	global_load_dwordx4 v[28:31], v228, s[10:11] offset:448
	global_load_dwordx4 v[32:35], v229, s[10:11] offset:0
	global_load_dwordx4 v[36:39], v229, s[10:11] offset:64
	global_load_dwordx4 v[40:43], v229, s[10:11] offset:128
	global_load_dwordx4 v[44:47], v229, s[10:11] offset:192
	global_load_dwordx4 v[48:51], v229, s[10:11] offset:256
	global_load_dwordx4 v[52:55], v229, s[10:11] offset:320
	global_load_dwordx4 v[56:59], v229, s[10:11] offset:384
	global_load_dwordx4 v[60:63], v229, s[10:11] offset:448
	global_load_dword v247, v230, s[12:13]
	global_load_dword v248, v230, s[12:13] offset:2048
	s_lshr_b32 s10, s1, 5
	s_sub_i32 s11, s1, 64
	s_lshr_b32 s11, s11, 4
	s_add_i32 s11, s11, 2
	s_cmp_lt_u32 s1, 64
	s_cselect_b32 s10, s10, s11
	s_lshl_b32 s11, s10, 19
	s_lshl_b32 s12, s0, 9
	s_add_u32 s11, s11, s12
	s_add_u32 s11, s11, 0x15040000
	s_add_u32 s6, s4, s11
	s_addc_u32 s7, s5, 0
	global_load_dwordx4 v[184:187], v224, s[6:7]
	s_add_u32 s6, s6, 0x8000
	s_addc_u32 s7, s7, 0
	global_load_dwordx4 v[188:191], v224, s[6:7]
	s_add_u32 s6, s6, 0x8000
	s_addc_u32 s7, s7, 0
	global_load_dwordx4 v[192:195], v224, s[6:7]
	s_add_u32 s6, s6, 0x8000
	s_addc_u32 s7, s7, 0
	global_load_dwordx4 v[196:199], v224, s[6:7]
	s_add_u32 s6, s6, 0x8000
	s_addc_u32 s7, s7, 0
	global_load_dwordx4 v[200:203], v224, s[6:7]
	s_add_u32 s6, s6, 0x8000
	s_addc_u32 s7, s7, 0
	global_load_dwordx4 v[204:207], v224, s[6:7]
	s_add_u32 s6, s6, 0x8000
	s_addc_u32 s7, s7, 0
	global_load_dwordx4 v[208:211], v224, s[6:7]
	s_add_u32 s6, s6, 0x8000
	s_addc_u32 s7, s7, 0
	global_load_dwordx4 v[212:215], v224, s[6:7]
.Lxa_unit:
	s_and_b32 s0, s69, 31
	s_lshr_b32 s1, s69, 8
	s_lshl_b32 s1, s1, 5
	s_add_i32 s1, s1, s0
	s_mul_i32 s0, s1, 2731
	s_lshr_b32 s0, s0, 16
	s_mul_i32 s17, s0, 24
	s_sub_i32 s1, s1, s17
	s_bfe_u32 s17, s69, 0x30005
	s_mul_i32 s17, s17, 24
	s_add_i32 s1, s1, s17
	s_lshr_b32 s10, s1, 5
	s_sub_i32 s11, s1, 64
	s_lshr_b32 s11, s11, 4
	s_add_i32 s11, s11, 2
	s_cmp_lt_u32 s1, 64
	s_cselect_b32 s10, s10, s11
	s_lshl_b32 s11, s10, 19
	s_lshl_b32 s12, s0, 9
	s_add_u32 s11, s11, s12
	s_add_u32 s11, s11, 0x15000000
	s_add_u32 s6, s4, s11
	s_addc_u32 s7, s5, 0
	s_mul_i32 s11, s0, 0x140000
	s_lshl_b32 s12, s10, 9
	s_add_u32 s11, s11, s12
	s_add_u32 s11, s11, 0x15800000
	s_add_u32 s8, s4, s11
	s_addc_u32 s9, s5, 0
	s_lshl_b32 s12, s1, 19
	s_lshl_b32 s13, s0, 9
	s_add_u32 s12, s12, s13
	s_add_u32 s12, s12, 0x9000000
	s_add_u32 s14, s4, s12
	s_addc_u32 s15, s5, 0
	global_load_dwordx4 v[128:131], v224, s[6:7]
	s_add_u32 s6, s6, 0x8000
	s_addc_u32 s7, s7, 0
	global_load_dwordx4 v[132:135], v224, s[6:7]
	s_add_u32 s6, s6, 0x8000
	s_addc_u32 s7, s7, 0
	global_load_dwordx4 v[136:139], v224, s[6:7]
	s_add_u32 s6, s6, 0x8000
	s_addc_u32 s7, s7, 0
	global_load_dwordx4 v[140:143], v224, s[6:7]
	s_add_u32 s6, s6, 0x8000
	s_addc_u32 s7, s7, 0
	global_load_dwordx4 v[144:147], v224, s[6:7]
	s_add_u32 s6, s6, 0x8000
	s_addc_u32 s7, s7, 0
	global_load_dwordx4 v[148:151], v224, s[6:7]
	s_add_u32 s6, s6, 0x8000
	s_addc_u32 s7, s7, 0
	global_load_dwordx4 v[152:155], v224, s[6:7]
	s_add_u32 s6, s6, 0x8000
	s_addc_u32 s7, s7, 0
	global_load_dwordx4 v[156:159], v224, s[6:7]
	s_add_u32 s6, s6, 0x8000
	s_addc_u32 s7, s7, 0
	s_waitcnt vmcnt(4)
	ds_write_b128 v226, v[128:131] offset:0
	ds_write_b128 v226, v[132:135] offset:8448
	ds_write_b128 v226, v[136:139] offset:16896
	ds_write_b128 v226, v[140:143] offset:25344
	s_waitcnt vmcnt(0)
	ds_write_b128 v226, v[144:147] offset:33792
	ds_write_b128 v226, v[148:151] offset:42240
	ds_write_b128 v226, v[152:155] offset:50688
	ds_write_b128 v226, v[156:159] offset:59136
	ds_write_b128 v227, v[184:187] offset:0
	ds_write_b128 v227, v[188:191] offset:8448
	ds_write_b128 v227, v[192:195] offset:16896
	ds_write_b128 v227, v[196:199] offset:25344
	ds_write_b128 v227, v[200:203] offset:33792
	ds_write_b128 v227, v[204:207] offset:42240
	ds_write_b128 v227, v[208:211] offset:50688
	ds_write_b128 v227, v[212:215] offset:59136
	s_waitcnt vmcnt(0)
	v_fmamk_f32 v178, v247, 0x3b800000, v181
	v_fmamk_f32 v179, v248, 0x3b800000, v181
	v_rsq_f32_e32 v178, v178
	v_rsq_f32_e32 v179, v179
	v_mov_b32_e32 v176, 0
	v_mov_b32_e32 v177, 0
	v_mul_f32_e32 v178, 0x3db8aa3b, v178
	v_mul_f32_e32 v179, 0x3db8aa3b, v179
	s_waitcnt lgkmcnt(0)
	s_barrier
	v_mov_b32_e32 v233, v231
	ds_read_b128 v[128:131], v233 offset:0
	ds_read_b128 v[132:135], v233 offset:64
	ds_read_b128 v[136:139], v233 offset:128
	ds_read_b128 v[140:143], v233 offset:192
	ds_read_b128 v[144:147], v233 offset:256
	ds_read_b128 v[148:151], v233 offset:320
	ds_read_b128 v[152:155], v233 offset:384
	ds_read_b128 v[156:159], v233 offset:448
	s_waitcnt lgkmcnt(0)
	ds_read_b128 v[184:187], v233 offset:8448
	ds_read_b128 v[188:191], v233 offset:8512
	ds_read_b128 v[192:195], v233 offset:8576
	ds_read_b128 v[196:199], v233 offset:8640
	ds_read_b128 v[200:203], v233 offset:8704
	ds_read_b128 v[204:207], v233 offset:8768
	ds_read_b128 v[208:211], v233 offset:8832
	ds_read_b128 v[212:215], v233 offset:8896
	v_mfma_f32_16x16x32_bf16 v[160:163], v[128:131], v[0:3], 0
	v_mfma_f32_16x16x32_bf16 v[164:167], v[128:131], v[32:35], 0
	v_mfma_f32_16x16x32_bf16 v[160:163], v[132:135], v[4:7], v[160:163]
	v_mfma_f32_16x16x32_bf16 v[164:167], v[132:135], v[36:39], v[164:167]
	v_mfma_f32_16x16x32_bf16 v[160:163], v[136:139], v[8:11], v[160:163]
	v_mfma_f32_16x16x32_bf16 v[164:167], v[136:139], v[40:43], v[164:167]
	v_mfma_f32_16x16x32_bf16 v[160:163], v[140:143], v[12:15], v[160:163]
	v_mfma_f32_16x16x32_bf16 v[164:167], v[140:143], v[44:47], v[164:167]
	v_mfma_f32_16x16x32_bf16 v[160:163], v[144:147], v[16:19], v[160:163]
	v_mfma_f32_16x16x32_bf16 v[164:167], v[144:147], v[48:51], v[164:167]
	v_mfma_f32_16x16x32_bf16 v[160:163], v[148:151], v[20:23], v[160:163]
	v_mfma_f32_16x16x32_bf16 v[164:167], v[148:151], v[52:55], v[164:167]
	v_mfma_f32_16x16x32_bf16 v[160:163], v[152:155], v[24:27], v[160:163]
	v_mfma_f32_16x16x32_bf16 v[164:167], v[152:155], v[56:59], v[164:167]
	v_mfma_f32_16x16x32_bf16 v[160:163], v[156:159], v[28:31], v[160:163]
	v_mfma_f32_16x16x32_bf16 v[164:167], v[156:159], v[60:63], v[164:167]
	s_waitcnt lgkmcnt(0)
	ds_read_b128 v[128:131], v233 offset:16896
	ds_read_b128 v[132:135], v233 offset:16960
	ds_read_b128 v[136:139], v233 offset:17024
	ds_read_b128 v[140:143], v233 offset:17088
	ds_read_b128 v[144:147], v233 offset:17152
	ds_read_b128 v[148:151], v233 offset:17216
	ds_read_b128 v[152:155], v233 offset:17280
	ds_read_b128 v[156:159], v233 offset:17344
	v_mfma_f32_16x16x32_bf16 v[168:171], v[184:187], v[0:3], 0
	v_fma_f32 v216, v160, v178, -v180
	v_fma_f32 v217, v161, v178, -v180
	v_mfma_f32_16x16x32_bf16 v[172:175], v[184:187], v[32:35], 0
	v_fma_f32 v218, v162, v178, -v180
	v_fma_f32 v219, v163, v178, -v180
	v_mfma_f32_16x16x32_bf16 v[168:171], v[188:191], v[4:7], v[168:171]
	v_exp_f32_e32 v216, v216
	v_exp_f32_e32 v217, v217
	v_mfma_f32_16x16x32_bf16 v[172:175], v[188:191], v[36:39], v[172:175]
	v_exp_f32_e32 v218, v218
	v_exp_f32_e32 v219, v219
	v_mfma_f32_16x16x32_bf16 v[168:171], v[192:195], v[8:11], v[168:171]
	v_fma_f32 v220, v164, v179, -v180
	v_fma_f32 v221, v165, v179, -v180
	v_mfma_f32_16x16x32_bf16 v[172:175], v[192:195], v[40:43], v[172:175]
	v_fma_f32 v222, v166, v179, -v180
	v_fma_f32 v223, v167, v179, -v180
	v_mfma_f32_16x16x32_bf16 v[168:171], v[196:199], v[12:15], v[168:171]
	v_exp_f32_e32 v220, v220
	v_exp_f32_e32 v221, v221
	v_mfma_f32_16x16x32_bf16 v[172:175], v[196:199], v[44:47], v[172:175]
	v_exp_f32_e32 v222, v222
	v_exp_f32_e32 v223, v223
	v_mfma_f32_16x16x32_bf16 v[168:171], v[200:203], v[16:19], v[168:171]
	v_add_f32_e32 v176, v176, v216
	v_add_f32_e32 v176, v176, v217
	v_mfma_f32_16x16x32_bf16 v[172:175], v[200:203], v[48:51], v[172:175]
	v_cvt_pk_bf16_f32 v64, v216, v217
	v_add_f32_e32 v176, v176, v218
	v_mfma_f32_16x16x32_bf16 v[168:171], v[204:207], v[20:23], v[168:171]
	v_add_f32_e32 v176, v176, v219
	v_cvt_pk_bf16_f32 v65, v218, v219
	v_mfma_f32_16x16x32_bf16 v[172:175], v[204:207], v[52:55], v[172:175]
	v_add_f32_e32 v177, v177, v220
	v_add_f32_e32 v177, v177, v221
	v_mfma_f32_16x16x32_bf16 v[168:171], v[208:211], v[24:27], v[168:171]
	v_cvt_pk_bf16_f32 v96, v220, v221
	v_add_f32_e32 v177, v177, v222
	v_mfma_f32_16x16x32_bf16 v[172:175], v[208:211], v[56:59], v[172:175]
	v_add_f32_e32 v177, v177, v223
	v_cvt_pk_bf16_f32 v97, v222, v223
	v_mfma_f32_16x16x32_bf16 v[168:171], v[212:215], v[28:31], v[168:171]
	v_mfma_f32_16x16x32_bf16 v[172:175], v[212:215], v[60:63], v[172:175]
	s_waitcnt lgkmcnt(0)
	ds_read_b128 v[184:187], v233 offset:25344
	ds_read_b128 v[188:191], v233 offset:25408
	ds_read_b128 v[192:195], v233 offset:25472
	ds_read_b128 v[196:199], v233 offset:25536
	ds_read_b128 v[200:203], v233 offset:25600
	ds_read_b128 v[204:207], v233 offset:25664
	ds_read_b128 v[208:211], v233 offset:25728
	ds_read_b128 v[212:215], v233 offset:25792
	v_mfma_f32_16x16x32_bf16 v[160:163], v[128:131], v[0:3], 0
	v_fma_f32 v216, v168, v178, -v180
	v_fma_f32 v217, v169, v178, -v180
	v_mfma_f32_16x16x32_bf16 v[164:167], v[128:131], v[32:35], 0
	v_fma_f32 v218, v170, v178, -v180
	v_fma_f32 v219, v171, v178, -v180
	v_mfma_f32_16x16x32_bf16 v[160:163], v[132:135], v[4:7], v[160:163]
	v_exp_f32_e32 v216, v216
	v_exp_f32_e32 v217, v217
	v_mfma_f32_16x16x32_bf16 v[164:167], v[132:135], v[36:39], v[164:167]
	v_exp_f32_e32 v218, v218
	v_exp_f32_e32 v219, v219
	v_mfma_f32_16x16x32_bf16 v[160:163], v[136:139], v[8:11], v[160:163]
	v_fma_f32 v220, v172, v179, -v180
	v_fma_f32 v221, v173, v179, -v180
	v_mfma_f32_16x16x32_bf16 v[164:167], v[136:139], v[40:43], v[164:167]
	v_fma_f32 v222, v174, v179, -v180
	v_fma_f32 v223, v175, v179, -v180
	v_mfma_f32_16x16x32_bf16 v[160:163], v[140:143], v[12:15], v[160:163]
	v_exp_f32_e32 v220, v220
	v_exp_f32_e32 v221, v221
	v_mfma_f32_16x16x32_bf16 v[164:167], v[140:143], v[44:47], v[164:167]
	v_exp_f32_e32 v222, v222
	v_exp_f32_e32 v223, v223
	v_mfma_f32_16x16x32_bf16 v[160:163], v[144:147], v[16:19], v[160:163]
	v_add_f32_e32 v176, v176, v216
	v_add_f32_e32 v176, v176, v217
	v_mfma_f32_16x16x32_bf16 v[164:167], v[144:147], v[48:51], v[164:167]
	v_cvt_pk_bf16_f32 v66, v216, v217
	v_add_f32_e32 v176, v176, v218
	v_mfma_f32_16x16x32_bf16 v[160:163], v[148:151], v[20:23], v[160:163]
	v_add_f32_e32 v176, v176, v219
	v_cvt_pk_bf16_f32 v67, v218, v219
	v_mfma_f32_16x16x32_bf16 v[164:167], v[148:151], v[52:55], v[164:167]
	v_add_f32_e32 v177, v177, v220
	v_add_f32_e32 v177, v177, v221
	v_mfma_f32_16x16x32_bf16 v[160:163], v[152:155], v[24:27], v[160:163]
	v_cvt_pk_bf16_f32 v98, v220, v221
	v_add_f32_e32 v177, v177, v222
	v_mfma_f32_16x16x32_bf16 v[164:167], v[152:155], v[56:59], v[164:167]
	v_add_f32_e32 v177, v177, v223
	v_cvt_pk_bf16_f32 v99, v222, v223
	v_mfma_f32_16x16x32_bf16 v[160:163], v[156:159], v[28:31], v[160:163]
	v_mfma_f32_16x16x32_bf16 v[164:167], v[156:159], v[60:63], v[164:167]
	s_waitcnt lgkmcnt(0)
	ds_read_b128 v[128:131], v233 offset:33792
	ds_read_b128 v[132:135], v233 offset:33856
	ds_read_b128 v[136:139], v233 offset:33920
	ds_read_b128 v[140:143], v233 offset:33984
	ds_read_b128 v[144:147], v233 offset:34048
	ds_read_b128 v[148:151], v233 offset:34112
	ds_read_b128 v[152:155], v233 offset:34176
	ds_read_b128 v[156:159], v233 offset:34240
	v_mfma_f32_16x16x32_bf16 v[168:171], v[184:187], v[0:3], 0
	v_fma_f32 v216, v160, v178, -v180
	v_fma_f32 v217, v161, v178, -v180
	v_mfma_f32_16x16x32_bf16 v[172:175], v[184:187], v[32:35], 0
	v_fma_f32 v218, v162, v178, -v180
	v_fma_f32 v219, v163, v178, -v180
	v_mfma_f32_16x16x32_bf16 v[168:171], v[188:191], v[4:7], v[168:171]
	v_exp_f32_e32 v216, v216
	v_exp_f32_e32 v217, v217
	v_mfma_f32_16x16x32_bf16 v[172:175], v[188:191], v[36:39], v[172:175]
	v_exp_f32_e32 v218, v218
	v_exp_f32_e32 v219, v219
	v_mfma_f32_16x16x32_bf16 v[168:171], v[192:195], v[8:11], v[168:171]
	v_fma_f32 v220, v164, v179, -v180
	v_fma_f32 v221, v165, v179, -v180
	v_mfma_f32_16x16x32_bf16 v[172:175], v[192:195], v[40:43], v[172:175]
	v_fma_f32 v222, v166, v179, -v180
	v_fma_f32 v223, v167, v179, -v180
	v_mfma_f32_16x16x32_bf16 v[168:171], v[196:199], v[12:15], v[168:171]
	v_exp_f32_e32 v220, v220
	v_exp_f32_e32 v221, v221
	v_mfma_f32_16x16x32_bf16 v[172:175], v[196:199], v[44:47], v[172:175]
	v_exp_f32_e32 v222, v222
	v_exp_f32_e32 v223, v223
	v_mfma_f32_16x16x32_bf16 v[168:171], v[200:203], v[16:19], v[168:171]
	v_add_f32_e32 v176, v176, v216
	v_add_f32_e32 v176, v176, v217
	v_mfma_f32_16x16x32_bf16 v[172:175], v[200:203], v[48:51], v[172:175]
	v_cvt_pk_bf16_f32 v68, v216, v217
	v_add_f32_e32 v176, v176, v218
	v_mfma_f32_16x16x32_bf16 v[168:171], v[204:207], v[20:23], v[168:171]
	v_add_f32_e32 v176, v176, v219
	v_cvt_pk_bf16_f32 v69, v218, v219
	v_mfma_f32_16x16x32_bf16 v[172:175], v[204:207], v[52:55], v[172:175]
	v_add_f32_e32 v177, v177, v220
	v_add_f32_e32 v177, v177, v221
	v_mfma_f32_16x16x32_bf16 v[168:171], v[208:211], v[24:27], v[168:171]
	v_cvt_pk_bf16_f32 v100, v220, v221
	v_add_f32_e32 v177, v177, v222
	v_mfma_f32_16x16x32_bf16 v[172:175], v[208:211], v[56:59], v[172:175]
	v_add_f32_e32 v177, v177, v223
	v_cvt_pk_bf16_f32 v101, v222, v223
	v_mfma_f32_16x16x32_bf16 v[168:171], v[212:215], v[28:31], v[168:171]
	v_mfma_f32_16x16x32_bf16 v[172:175], v[212:215], v[60:63], v[172:175]
	s_waitcnt lgkmcnt(0)
	ds_read_b128 v[184:187], v233 offset:42240
	ds_read_b128 v[188:191], v233 offset:42304
	ds_read_b128 v[192:195], v233 offset:42368
	ds_read_b128 v[196:199], v233 offset:42432
	ds_read_b128 v[200:203], v233 offset:42496
	ds_read_b128 v[204:207], v233 offset:42560
	ds_read_b128 v[208:211], v233 offset:42624
	ds_read_b128 v[212:215], v233 offset:42688
	v_mfma_f32_16x16x32_bf16 v[160:163], v[128:131], v[0:3], 0
	v_fma_f32 v216, v168, v178, -v180
	v_fma_f32 v217, v169, v178, -v180
	v_mfma_f32_16x16x32_bf16 v[164:167], v[128:131], v[32:35], 0
	v_fma_f32 v218, v170, v178, -v180
	v_fma_f32 v219, v171, v178, -v180
	v_mfma_f32_16x16x32_bf16 v[160:163], v[132:135], v[4:7], v[160:163]
	v_exp_f32_e32 v216, v216
	v_exp_f32_e32 v217, v217
	v_mfma_f32_16x16x32_bf16 v[164:167], v[132:135], v[36:39], v[164:167]
	v_exp_f32_e32 v218, v218
	v_exp_f32_e32 v219, v219
	v_mfma_f32_16x16x32_bf16 v[160:163], v[136:139], v[8:11], v[160:163]
	v_fma_f32 v220, v172, v179, -v180
	v_fma_f32 v221, v173, v179, -v180
	v_mfma_f32_16x16x32_bf16 v[164:167], v[136:139], v[40:43], v[164:167]
	v_fma_f32 v222, v174, v179, -v180
	v_fma_f32 v223, v175, v179, -v180
	v_mfma_f32_16x16x32_bf16 v[160:163], v[140:143], v[12:15], v[160:163]
	v_exp_f32_e32 v220, v220
	v_exp_f32_e32 v221, v221
	v_mfma_f32_16x16x32_bf16 v[164:167], v[140:143], v[44:47], v[164:167]
	v_exp_f32_e32 v222, v222
	v_exp_f32_e32 v223, v223
	v_mfma_f32_16x16x32_bf16 v[160:163], v[144:147], v[16:19], v[160:163]
	v_add_f32_e32 v176, v176, v216
	v_add_f32_e32 v176, v176, v217
	v_mfma_f32_16x16x32_bf16 v[164:167], v[144:147], v[48:51], v[164:167]
	v_cvt_pk_bf16_f32 v70, v216, v217
	v_add_f32_e32 v176, v176, v218
	v_mfma_f32_16x16x32_bf16 v[160:163], v[148:151], v[20:23], v[160:163]
	v_add_f32_e32 v176, v176, v219
	v_cvt_pk_bf16_f32 v71, v218, v219
	v_mfma_f32_16x16x32_bf16 v[164:167], v[148:151], v[52:55], v[164:167]
	v_add_f32_e32 v177, v177, v220
	v_add_f32_e32 v177, v177, v221
	v_mfma_f32_16x16x32_bf16 v[160:163], v[152:155], v[24:27], v[160:163]
	v_cvt_pk_bf16_f32 v102, v220, v221
	v_add_f32_e32 v177, v177, v222
	v_mfma_f32_16x16x32_bf16 v[164:167], v[152:155], v[56:59], v[164:167]
	v_add_f32_e32 v177, v177, v223
	v_cvt_pk_bf16_f32 v103, v222, v223
	v_mfma_f32_16x16x32_bf16 v[160:163], v[156:159], v[28:31], v[160:163]
	v_mfma_f32_16x16x32_bf16 v[164:167], v[156:159], v[60:63], v[164:167]
	s_waitcnt lgkmcnt(0)
	ds_read_b128 v[128:131], v233 offset:50688
	ds_read_b128 v[132:135], v233 offset:50752
	ds_read_b128 v[136:139], v233 offset:50816
	ds_read_b128 v[140:143], v233 offset:50880
	ds_read_b128 v[144:147], v233 offset:50944
	ds_read_b128 v[148:151], v233 offset:51008
	ds_read_b128 v[152:155], v233 offset:51072
	ds_read_b128 v[156:159], v233 offset:51136
	v_mfma_f32_16x16x32_bf16 v[168:171], v[184:187], v[0:3], 0
	v_fma_f32 v216, v160, v178, -v180
	v_fma_f32 v217, v161, v178, -v180
	v_mfma_f32_16x16x32_bf16 v[172:175], v[184:187], v[32:35], 0
	v_fma_f32 v218, v162, v178, -v180
	v_fma_f32 v219, v163, v178, -v180
	v_mfma_f32_16x16x32_bf16 v[168:171], v[188:191], v[4:7], v[168:171]
	v_exp_f32_e32 v216, v216
	v_exp_f32_e32 v217, v217
	v_mfma_f32_16x16x32_bf16 v[172:175], v[188:191], v[36:39], v[172:175]
	v_exp_f32_e32 v218, v218
	v_exp_f32_e32 v219, v219
	v_mfma_f32_16x16x32_bf16 v[168:171], v[192:195], v[8:11], v[168:171]
	v_fma_f32 v220, v164, v179, -v180
	v_fma_f32 v221, v165, v179, -v180
	v_mfma_f32_16x16x32_bf16 v[172:175], v[192:195], v[40:43], v[172:175]
	v_fma_f32 v222, v166, v179, -v180
	v_fma_f32 v223, v167, v179, -v180
	v_mfma_f32_16x16x32_bf16 v[168:171], v[196:199], v[12:15], v[168:171]
	v_exp_f32_e32 v220, v220
	v_exp_f32_e32 v221, v221
	v_mfma_f32_16x16x32_bf16 v[172:175], v[196:199], v[44:47], v[172:175]
	v_exp_f32_e32 v222, v222
	v_exp_f32_e32 v223, v223
	v_mfma_f32_16x16x32_bf16 v[168:171], v[200:203], v[16:19], v[168:171]
	v_add_f32_e32 v176, v176, v216
	v_add_f32_e32 v176, v176, v217
	v_mfma_f32_16x16x32_bf16 v[172:175], v[200:203], v[48:51], v[172:175]
	v_cvt_pk_bf16_f32 v72, v216, v217
	v_add_f32_e32 v176, v176, v218
	v_mfma_f32_16x16x32_bf16 v[168:171], v[204:207], v[20:23], v[168:171]
	v_add_f32_e32 v176, v176, v219
	v_cvt_pk_bf16_f32 v73, v218, v219
	v_mfma_f32_16x16x32_bf16 v[172:175], v[204:207], v[52:55], v[172:175]
	v_add_f32_e32 v177, v177, v220
	v_add_f32_e32 v177, v177, v221
	v_mfma_f32_16x16x32_bf16 v[168:171], v[208:211], v[24:27], v[168:171]
	v_cvt_pk_bf16_f32 v104, v220, v221
	v_add_f32_e32 v177, v177, v222
	v_mfma_f32_16x16x32_bf16 v[172:175], v[208:211], v[56:59], v[172:175]
	v_add_f32_e32 v177, v177, v223
	v_cvt_pk_bf16_f32 v105, v222, v223
	v_mfma_f32_16x16x32_bf16 v[168:171], v[212:215], v[28:31], v[168:171]
	v_mfma_f32_16x16x32_bf16 v[172:175], v[212:215], v[60:63], v[172:175]
	s_waitcnt lgkmcnt(0)
	v_add_u32_e32 v233, 59136, v233
	ds_read_b128 v[184:187], v233 offset:0
	ds_read_b128 v[188:191], v233 offset:64
	ds_read_b128 v[192:195], v233 offset:128
	ds_read_b128 v[196:199], v233 offset:192
	ds_read_b128 v[200:203], v233 offset:256
	ds_read_b128 v[204:207], v233 offset:320
	ds_read_b128 v[208:211], v233 offset:384
	ds_read_b128 v[212:215], v233 offset:448
	v_mfma_f32_16x16x32_bf16 v[160:163], v[128:131], v[0:3], 0
	v_fma_f32 v216, v168, v178, -v180
	v_fma_f32 v217, v169, v178, -v180
	v_mfma_f32_16x16x32_bf16 v[164:167], v[128:131], v[32:35], 0
	v_fma_f32 v218, v170, v178, -v180
	v_fma_f32 v219, v171, v178, -v180
	v_mfma_f32_16x16x32_bf16 v[160:163], v[132:135], v[4:7], v[160:163]
	v_exp_f32_e32 v216, v216
	v_exp_f32_e32 v217, v217
	v_mfma_f32_16x16x32_bf16 v[164:167], v[132:135], v[36:39], v[164:167]
	v_exp_f32_e32 v218, v218
	v_exp_f32_e32 v219, v219
	v_mfma_f32_16x16x32_bf16 v[160:163], v[136:139], v[8:11], v[160:163]
	v_fma_f32 v220, v172, v179, -v180
	v_fma_f32 v221, v173, v179, -v180
	v_mfma_f32_16x16x32_bf16 v[164:167], v[136:139], v[40:43], v[164:167]
	v_fma_f32 v222, v174, v179, -v180
	v_fma_f32 v223, v175, v179, -v180
	v_mfma_f32_16x16x32_bf16 v[160:163], v[140:143], v[12:15], v[160:163]
	v_exp_f32_e32 v220, v220
	v_exp_f32_e32 v221, v221
	v_mfma_f32_16x16x32_bf16 v[164:167], v[140:143], v[44:47], v[164:167]
	v_exp_f32_e32 v222, v222
	v_exp_f32_e32 v223, v223
	v_mfma_f32_16x16x32_bf16 v[160:163], v[144:147], v[16:19], v[160:163]
	v_add_f32_e32 v176, v176, v216
	v_add_f32_e32 v176, v176, v217
	v_mfma_f32_16x16x32_bf16 v[164:167], v[144:147], v[48:51], v[164:167]
	v_cvt_pk_bf16_f32 v74, v216, v217
	v_add_f32_e32 v176, v176, v218
	v_mfma_f32_16x16x32_bf16 v[160:163], v[148:151], v[20:23], v[160:163]
	v_add_f32_e32 v176, v176, v219
	v_cvt_pk_bf16_f32 v75, v218, v219
	v_mfma_f32_16x16x32_bf16 v[164:167], v[148:151], v[52:55], v[164:167]
	v_add_f32_e32 v177, v177, v220
	v_add_f32_e32 v177, v177, v221
	v_mfma_f32_16x16x32_bf16 v[160:163], v[152:155], v[24:27], v[160:163]
	v_cvt_pk_bf16_f32 v106, v220, v221
	v_add_f32_e32 v177, v177, v222
	v_mfma_f32_16x16x32_bf16 v[164:167], v[152:155], v[56:59], v[164:167]
	v_add_f32_e32 v177, v177, v223
	v_cvt_pk_bf16_f32 v107, v222, v223
	v_mfma_f32_16x16x32_bf16 v[160:163], v[156:159], v[28:31], v[160:163]
	v_mfma_f32_16x16x32_bf16 v[164:167], v[156:159], v[60:63], v[164:167]
	s_waitcnt lgkmcnt(0)
	ds_read_b128 v[128:131], v233 offset:8448
	ds_read_b128 v[132:135], v233 offset:8512
	ds_read_b128 v[136:139], v233 offset:8576
	ds_read_b128 v[140:143], v233 offset:8640
	ds_read_b128 v[144:147], v233 offset:8704
	ds_read_b128 v[148:151], v233 offset:8768
	ds_read_b128 v[152:155], v233 offset:8832
	ds_read_b128 v[156:159], v233 offset:8896
	v_mfma_f32_16x16x32_bf16 v[168:171], v[184:187], v[0:3], 0
	v_fma_f32 v216, v160, v178, -v180
	v_fma_f32 v217, v161, v178, -v180
	v_mfma_f32_16x16x32_bf16 v[172:175], v[184:187], v[32:35], 0
	v_fma_f32 v218, v162, v178, -v180
	v_fma_f32 v219, v163, v178, -v180
	v_mfma_f32_16x16x32_bf16 v[168:171], v[188:191], v[4:7], v[168:171]
	v_exp_f32_e32 v216, v216
	v_exp_f32_e32 v217, v217
	v_mfma_f32_16x16x32_bf16 v[172:175], v[188:191], v[36:39], v[172:175]
	v_exp_f32_e32 v218, v218
	v_exp_f32_e32 v219, v219
	v_mfma_f32_16x16x32_bf16 v[168:171], v[192:195], v[8:11], v[168:171]
	v_fma_f32 v220, v164, v179, -v180
	v_fma_f32 v221, v165, v179, -v180
	v_mfma_f32_16x16x32_bf16 v[172:175], v[192:195], v[40:43], v[172:175]
	v_fma_f32 v222, v166, v179, -v180
	v_fma_f32 v223, v167, v179, -v180
	v_mfma_f32_16x16x32_bf16 v[168:171], v[196:199], v[12:15], v[168:171]
	v_exp_f32_e32 v220, v220
	v_exp_f32_e32 v221, v221
	v_mfma_f32_16x16x32_bf16 v[172:175], v[196:199], v[44:47], v[172:175]
	v_exp_f32_e32 v222, v222
	v_exp_f32_e32 v223, v223
	v_mfma_f32_16x16x32_bf16 v[168:171], v[200:203], v[16:19], v[168:171]
	v_add_f32_e32 v176, v176, v216
	v_add_f32_e32 v176, v176, v217
	v_mfma_f32_16x16x32_bf16 v[172:175], v[200:203], v[48:51], v[172:175]
	v_cvt_pk_bf16_f32 v76, v216, v217
	v_add_f32_e32 v176, v176, v218
	v_mfma_f32_16x16x32_bf16 v[168:171], v[204:207], v[20:23], v[168:171]
	v_add_f32_e32 v176, v176, v219
	v_cvt_pk_bf16_f32 v77, v218, v219
	v_mfma_f32_16x16x32_bf16 v[172:175], v[204:207], v[52:55], v[172:175]
	v_add_f32_e32 v177, v177, v220
	v_add_f32_e32 v177, v177, v221
	v_mfma_f32_16x16x32_bf16 v[168:171], v[208:211], v[24:27], v[168:171]
	v_cvt_pk_bf16_f32 v108, v220, v221
	v_add_f32_e32 v177, v177, v222
	v_mfma_f32_16x16x32_bf16 v[172:175], v[208:211], v[56:59], v[172:175]
	v_add_f32_e32 v177, v177, v223
	v_cvt_pk_bf16_f32 v109, v222, v223
	v_mfma_f32_16x16x32_bf16 v[168:171], v[212:215], v[28:31], v[168:171]
	v_mfma_f32_16x16x32_bf16 v[172:175], v[212:215], v[60:63], v[172:175]
	s_waitcnt lgkmcnt(0)
	ds_read_b128 v[184:187], v233 offset:16896
	ds_read_b128 v[188:191], v233 offset:16960
	ds_read_b128 v[192:195], v233 offset:17024
	ds_read_b128 v[196:199], v233 offset:17088
	ds_read_b128 v[200:203], v233 offset:17152
	ds_read_b128 v[204:207], v233 offset:17216
	ds_read_b128 v[208:211], v233 offset:17280
	ds_read_b128 v[212:215], v233 offset:17344
	v_mfma_f32_16x16x32_bf16 v[160:163], v[128:131], v[0:3], 0
	v_fma_f32 v216, v168, v178, -v180
	v_fma_f32 v217, v169, v178, -v180
	v_mfma_f32_16x16x32_bf16 v[164:167], v[128:131], v[32:35], 0
	v_fma_f32 v218, v170, v178, -v180
	v_fma_f32 v219, v171, v178, -v180
	v_mfma_f32_16x16x32_bf16 v[160:163], v[132:135], v[4:7], v[160:163]
	v_exp_f32_e32 v216, v216
	v_exp_f32_e32 v217, v217
	v_mfma_f32_16x16x32_bf16 v[164:167], v[132:135], v[36:39], v[164:167]
	v_exp_f32_e32 v218, v218
	v_exp_f32_e32 v219, v219
	v_mfma_f32_16x16x32_bf16 v[160:163], v[136:139], v[8:11], v[160:163]
	v_fma_f32 v220, v172, v179, -v180
	v_fma_f32 v221, v173, v179, -v180
	v_mfma_f32_16x16x32_bf16 v[164:167], v[136:139], v[40:43], v[164:167]
	v_fma_f32 v222, v174, v179, -v180
	v_fma_f32 v223, v175, v179, -v180
	v_mfma_f32_16x16x32_bf16 v[160:163], v[140:143], v[12:15], v[160:163]
	v_exp_f32_e32 v220, v220
	v_exp_f32_e32 v221, v221
	v_mfma_f32_16x16x32_bf16 v[164:167], v[140:143], v[44:47], v[164:167]
	v_exp_f32_e32 v222, v222
	v_exp_f32_e32 v223, v223
	v_mfma_f32_16x16x32_bf16 v[160:163], v[144:147], v[16:19], v[160:163]
	v_add_f32_e32 v176, v176, v216
	v_add_f32_e32 v176, v176, v217
	v_mfma_f32_16x16x32_bf16 v[164:167], v[144:147], v[48:51], v[164:167]
	v_cvt_pk_bf16_f32 v78, v216, v217
	v_add_f32_e32 v176, v176, v218
	v_mfma_f32_16x16x32_bf16 v[160:163], v[148:151], v[20:23], v[160:163]
	v_add_f32_e32 v176, v176, v219
	v_cvt_pk_bf16_f32 v79, v218, v219
	v_mfma_f32_16x16x32_bf16 v[164:167], v[148:151], v[52:55], v[164:167]
	v_add_f32_e32 v177, v177, v220
	v_add_f32_e32 v177, v177, v221
	v_mfma_f32_16x16x32_bf16 v[160:163], v[152:155], v[24:27], v[160:163]
	v_cvt_pk_bf16_f32 v110, v220, v221
	v_add_f32_e32 v177, v177, v222
	v_mfma_f32_16x16x32_bf16 v[164:167], v[152:155], v[56:59], v[164:167]
	v_add_f32_e32 v177, v177, v223
	v_cvt_pk_bf16_f32 v111, v222, v223
	v_mfma_f32_16x16x32_bf16 v[160:163], v[156:159], v[28:31], v[160:163]
	v_mfma_f32_16x16x32_bf16 v[164:167], v[156:159], v[60:63], v[164:167]
	s_waitcnt lgkmcnt(0)
	ds_read_b128 v[128:131], v233 offset:25344
	ds_read_b128 v[132:135], v233 offset:25408
	ds_read_b128 v[136:139], v233 offset:25472
	ds_read_b128 v[140:143], v233 offset:25536
	ds_read_b128 v[144:147], v233 offset:25600
	ds_read_b128 v[148:151], v233 offset:25664
	ds_read_b128 v[152:155], v233 offset:25728
	ds_read_b128 v[156:159], v233 offset:25792
	v_mfma_f32_16x16x32_bf16 v[168:171], v[184:187], v[0:3], 0
	v_fma_f32 v216, v160, v178, -v180
	v_fma_f32 v217, v161, v178, -v180
	v_mfma_f32_16x16x32_bf16 v[172:175], v[184:187], v[32:35], 0
	v_fma_f32 v218, v162, v178, -v180
	v_fma_f32 v219, v163, v178, -v180
	v_mfma_f32_16x16x32_bf16 v[168:171], v[188:191], v[4:7], v[168:171]
	v_exp_f32_e32 v216, v216
	v_exp_f32_e32 v217, v217
	v_mfma_f32_16x16x32_bf16 v[172:175], v[188:191], v[36:39], v[172:175]
	v_exp_f32_e32 v218, v218
	v_exp_f32_e32 v219, v219
	v_mfma_f32_16x16x32_bf16 v[168:171], v[192:195], v[8:11], v[168:171]
	v_fma_f32 v220, v164, v179, -v180
	v_fma_f32 v221, v165, v179, -v180
	v_mfma_f32_16x16x32_bf16 v[172:175], v[192:195], v[40:43], v[172:175]
	v_fma_f32 v222, v166, v179, -v180
	v_fma_f32 v223, v167, v179, -v180
	v_mfma_f32_16x16x32_bf16 v[168:171], v[196:199], v[12:15], v[168:171]
	v_exp_f32_e32 v220, v220
	v_exp_f32_e32 v221, v221
	v_mfma_f32_16x16x32_bf16 v[172:175], v[196:199], v[44:47], v[172:175]
	v_exp_f32_e32 v222, v222
	v_exp_f32_e32 v223, v223
	v_mfma_f32_16x16x32_bf16 v[168:171], v[200:203], v[16:19], v[168:171]
	v_add_f32_e32 v176, v176, v216
	v_add_f32_e32 v176, v176, v217
	v_mfma_f32_16x16x32_bf16 v[172:175], v[200:203], v[48:51], v[172:175]
	v_cvt_pk_bf16_f32 v80, v216, v217
	v_add_f32_e32 v176, v176, v218
	v_mfma_f32_16x16x32_bf16 v[168:171], v[204:207], v[20:23], v[168:171]
	v_add_f32_e32 v176, v176, v219
	v_cvt_pk_bf16_f32 v81, v218, v219
	v_mfma_f32_16x16x32_bf16 v[172:175], v[204:207], v[52:55], v[172:175]
	v_add_f32_e32 v177, v177, v220
	v_add_f32_e32 v177, v177, v221
	v_mfma_f32_16x16x32_bf16 v[168:171], v[208:211], v[24:27], v[168:171]
	v_cvt_pk_bf16_f32 v112, v220, v221
	v_add_f32_e32 v177, v177, v222
	v_mfma_f32_16x16x32_bf16 v[172:175], v[208:211], v[56:59], v[172:175]
	v_add_f32_e32 v177, v177, v223
	v_cvt_pk_bf16_f32 v113, v222, v223
	v_mfma_f32_16x16x32_bf16 v[168:171], v[212:215], v[28:31], v[168:171]
	v_mfma_f32_16x16x32_bf16 v[172:175], v[212:215], v[60:63], v[172:175]
	s_waitcnt lgkmcnt(0)
	ds_read_b128 v[184:187], v233 offset:33792
	ds_read_b128 v[188:191], v233 offset:33856
	ds_read_b128 v[192:195], v233 offset:33920
	ds_read_b128 v[196:199], v233 offset:33984
	ds_read_b128 v[200:203], v233 offset:34048
	ds_read_b128 v[204:207], v233 offset:34112
	ds_read_b128 v[208:211], v233 offset:34176
	ds_read_b128 v[212:215], v233 offset:34240
	v_mfma_f32_16x16x32_bf16 v[160:163], v[128:131], v[0:3], 0
	v_fma_f32 v216, v168, v178, -v180
	v_fma_f32 v217, v169, v178, -v180
	v_mfma_f32_16x16x32_bf16 v[164:167], v[128:131], v[32:35], 0
	v_fma_f32 v218, v170, v178, -v180
	v_fma_f32 v219, v171, v178, -v180
	v_mfma_f32_16x16x32_bf16 v[160:163], v[132:135], v[4:7], v[160:163]
	v_exp_f32_e32 v216, v216
	v_exp_f32_e32 v217, v217
	v_mfma_f32_16x16x32_bf16 v[164:167], v[132:135], v[36:39], v[164:167]
	v_exp_f32_e32 v218, v218
	v_exp_f32_e32 v219, v219
	v_mfma_f32_16x16x32_bf16 v[160:163], v[136:139], v[8:11], v[160:163]
	v_fma_f32 v220, v172, v179, -v180
	v_fma_f32 v221, v173, v179, -v180
	v_mfma_f32_16x16x32_bf16 v[164:167], v[136:139], v[40:43], v[164:167]
	v_fma_f32 v222, v174, v179, -v180
	v_fma_f32 v223, v175, v179, -v180
	v_mfma_f32_16x16x32_bf16 v[160:163], v[140:143], v[12:15], v[160:163]
	v_exp_f32_e32 v220, v220
	v_exp_f32_e32 v221, v221
	v_mfma_f32_16x16x32_bf16 v[164:167], v[140:143], v[44:47], v[164:167]
	v_exp_f32_e32 v222, v222
	v_exp_f32_e32 v223, v223
	v_mfma_f32_16x16x32_bf16 v[160:163], v[144:147], v[16:19], v[160:163]
	v_add_f32_e32 v176, v176, v216
	v_add_f32_e32 v176, v176, v217
	v_mfma_f32_16x16x32_bf16 v[164:167], v[144:147], v[48:51], v[164:167]
	v_cvt_pk_bf16_f32 v82, v216, v217
	v_add_f32_e32 v176, v176, v218
	v_mfma_f32_16x16x32_bf16 v[160:163], v[148:151], v[20:23], v[160:163]
	v_add_f32_e32 v176, v176, v219
	v_cvt_pk_bf16_f32 v83, v218, v219
	v_mfma_f32_16x16x32_bf16 v[164:167], v[148:151], v[52:55], v[164:167]
	v_add_f32_e32 v177, v177, v220
	v_add_f32_e32 v177, v177, v221
	v_mfma_f32_16x16x32_bf16 v[160:163], v[152:155], v[24:27], v[160:163]
	v_cvt_pk_bf16_f32 v114, v220, v221
	v_add_f32_e32 v177, v177, v222
	v_mfma_f32_16x16x32_bf16 v[164:167], v[152:155], v[56:59], v[164:167]
	v_add_f32_e32 v177, v177, v223
	v_cvt_pk_bf16_f32 v115, v222, v223
	v_mfma_f32_16x16x32_bf16 v[160:163], v[156:159], v[28:31], v[160:163]
	v_mfma_f32_16x16x32_bf16 v[164:167], v[156:159], v[60:63], v[164:167]
	s_waitcnt lgkmcnt(0)
	ds_read_b128 v[128:131], v233 offset:42240
	ds_read_b128 v[132:135], v233 offset:42304
	ds_read_b128 v[136:139], v233 offset:42368
	ds_read_b128 v[140:143], v233 offset:42432
	ds_read_b128 v[144:147], v233 offset:42496
	ds_read_b128 v[148:151], v233 offset:42560
	ds_read_b128 v[152:155], v233 offset:42624
	ds_read_b128 v[156:159], v233 offset:42688
	v_mfma_f32_16x16x32_bf16 v[168:171], v[184:187], v[0:3], 0
	v_fma_f32 v216, v160, v178, -v180
	v_fma_f32 v217, v161, v178, -v180
	v_mfma_f32_16x16x32_bf16 v[172:175], v[184:187], v[32:35], 0
	v_fma_f32 v218, v162, v178, -v180
	v_fma_f32 v219, v163, v178, -v180
	v_mfma_f32_16x16x32_bf16 v[168:171], v[188:191], v[4:7], v[168:171]
	v_exp_f32_e32 v216, v216
	v_exp_f32_e32 v217, v217
	v_mfma_f32_16x16x32_bf16 v[172:175], v[188:191], v[36:39], v[172:175]
	v_exp_f32_e32 v218, v218
	v_exp_f32_e32 v219, v219
	v_mfma_f32_16x16x32_bf16 v[168:171], v[192:195], v[8:11], v[168:171]
	v_fma_f32 v220, v164, v179, -v180
	v_fma_f32 v221, v165, v179, -v180
	v_mfma_f32_16x16x32_bf16 v[172:175], v[192:195], v[40:43], v[172:175]
	v_fma_f32 v222, v166, v179, -v180
	v_fma_f32 v223, v167, v179, -v180
	v_mfma_f32_16x16x32_bf16 v[168:171], v[196:199], v[12:15], v[168:171]
	v_exp_f32_e32 v220, v220
	v_exp_f32_e32 v221, v221
	v_mfma_f32_16x16x32_bf16 v[172:175], v[196:199], v[44:47], v[172:175]
	v_exp_f32_e32 v222, v222
	v_exp_f32_e32 v223, v223
	v_mfma_f32_16x16x32_bf16 v[168:171], v[200:203], v[16:19], v[168:171]
	v_add_f32_e32 v176, v176, v216
	v_add_f32_e32 v176, v176, v217
	v_mfma_f32_16x16x32_bf16 v[172:175], v[200:203], v[48:51], v[172:175]
	v_cvt_pk_bf16_f32 v84, v216, v217
	v_add_f32_e32 v176, v176, v218
	v_mfma_f32_16x16x32_bf16 v[168:171], v[204:207], v[20:23], v[168:171]
	v_add_f32_e32 v176, v176, v219
	v_cvt_pk_bf16_f32 v85, v218, v219
	v_mfma_f32_16x16x32_bf16 v[172:175], v[204:207], v[52:55], v[172:175]
	v_add_f32_e32 v177, v177, v220
	v_add_f32_e32 v177, v177, v221
	v_mfma_f32_16x16x32_bf16 v[168:171], v[208:211], v[24:27], v[168:171]
	v_cvt_pk_bf16_f32 v116, v220, v221
	v_add_f32_e32 v177, v177, v222
	v_mfma_f32_16x16x32_bf16 v[172:175], v[208:211], v[56:59], v[172:175]
	v_add_f32_e32 v177, v177, v223
	v_cvt_pk_bf16_f32 v117, v222, v223
	v_mfma_f32_16x16x32_bf16 v[168:171], v[212:215], v[28:31], v[168:171]
	v_mfma_f32_16x16x32_bf16 v[172:175], v[212:215], v[60:63], v[172:175]
	s_waitcnt lgkmcnt(0)
	ds_read_b128 v[184:187], v233 offset:50688
	ds_read_b128 v[188:191], v233 offset:50752
	ds_read_b128 v[192:195], v233 offset:50816
	ds_read_b128 v[196:199], v233 offset:50880
	ds_read_b128 v[200:203], v233 offset:50944
	ds_read_b128 v[204:207], v233 offset:51008
	ds_read_b128 v[208:211], v233 offset:51072
	ds_read_b128 v[212:215], v233 offset:51136
	v_mfma_f32_16x16x32_bf16 v[160:163], v[128:131], v[0:3], 0
	v_fma_f32 v216, v168, v178, -v180
	v_fma_f32 v217, v169, v178, -v180
	v_mfma_f32_16x16x32_bf16 v[164:167], v[128:131], v[32:35], 0
	v_fma_f32 v218, v170, v178, -v180
	v_fma_f32 v219, v171, v178, -v180
	v_mfma_f32_16x16x32_bf16 v[160:163], v[132:135], v[4:7], v[160:163]
	v_exp_f32_e32 v216, v216
	v_exp_f32_e32 v217, v217
	v_mfma_f32_16x16x32_bf16 v[164:167], v[132:135], v[36:39], v[164:167]
	v_exp_f32_e32 v218, v218
	v_exp_f32_e32 v219, v219
	v_mfma_f32_16x16x32_bf16 v[160:163], v[136:139], v[8:11], v[160:163]
	v_fma_f32 v220, v172, v179, -v180
	v_fma_f32 v221, v173, v179, -v180
	v_mfma_f32_16x16x32_bf16 v[164:167], v[136:139], v[40:43], v[164:167]
	v_fma_f32 v222, v174, v179, -v180
	v_fma_f32 v223, v175, v179, -v180
	v_mfma_f32_16x16x32_bf16 v[160:163], v[140:143], v[12:15], v[160:163]
	v_exp_f32_e32 v220, v220
	v_exp_f32_e32 v221, v221
	v_mfma_f32_16x16x32_bf16 v[164:167], v[140:143], v[44:47], v[164:167]
	v_exp_f32_e32 v222, v222
	v_exp_f32_e32 v223, v223
	v_mfma_f32_16x16x32_bf16 v[160:163], v[144:147], v[16:19], v[160:163]
	v_add_f32_e32 v176, v176, v216
	v_add_f32_e32 v176, v176, v217
	v_mfma_f32_16x16x32_bf16 v[164:167], v[144:147], v[48:51], v[164:167]
	v_cvt_pk_bf16_f32 v86, v216, v217
	v_add_f32_e32 v176, v176, v218
	v_mfma_f32_16x16x32_bf16 v[160:163], v[148:151], v[20:23], v[160:163]
	v_add_f32_e32 v176, v176, v219
	v_cvt_pk_bf16_f32 v87, v218, v219
	v_mfma_f32_16x16x32_bf16 v[164:167], v[148:151], v[52:55], v[164:167]
	v_add_f32_e32 v177, v177, v220
	v_add_f32_e32 v177, v177, v221
	v_mfma_f32_16x16x32_bf16 v[160:163], v[152:155], v[24:27], v[160:163]
	v_cvt_pk_bf16_f32 v118, v220, v221
	v_add_f32_e32 v177, v177, v222
	v_mfma_f32_16x16x32_bf16 v[164:167], v[152:155], v[56:59], v[164:167]
	v_add_f32_e32 v177, v177, v223
	v_cvt_pk_bf16_f32 v119, v222, v223
	v_mfma_f32_16x16x32_bf16 v[160:163], v[156:159], v[28:31], v[160:163]
	v_mfma_f32_16x16x32_bf16 v[164:167], v[156:159], v[60:63], v[164:167]
	s_waitcnt lgkmcnt(0)
	v_add_u32_e32 v233, 59136, v233
	ds_read_b128 v[128:131], v233 offset:0
	ds_read_b128 v[132:135], v233 offset:64
	ds_read_b128 v[136:139], v233 offset:128
	ds_read_b128 v[140:143], v233 offset:192
	ds_read_b128 v[144:147], v233 offset:256
	ds_read_b128 v[148:151], v233 offset:320
	ds_read_b128 v[152:155], v233 offset:384
	ds_read_b128 v[156:159], v233 offset:448
	v_mfma_f32_16x16x32_bf16 v[168:171], v[184:187], v[0:3], 0
	v_fma_f32 v216, v160, v178, -v180
	v_fma_f32 v217, v161, v178, -v180
	v_mfma_f32_16x16x32_bf16 v[172:175], v[184:187], v[32:35], 0
	v_fma_f32 v218, v162, v178, -v180
	v_fma_f32 v219, v163, v178, -v180
	v_mfma_f32_16x16x32_bf16 v[168:171], v[188:191], v[4:7], v[168:171]
	v_exp_f32_e32 v216, v216
	v_exp_f32_e32 v217, v217
	v_mfma_f32_16x16x32_bf16 v[172:175], v[188:191], v[36:39], v[172:175]
	v_exp_f32_e32 v218, v218
	v_exp_f32_e32 v219, v219
	v_mfma_f32_16x16x32_bf16 v[168:171], v[192:195], v[8:11], v[168:171]
	v_fma_f32 v220, v164, v179, -v180
	v_fma_f32 v221, v165, v179, -v180
	v_mfma_f32_16x16x32_bf16 v[172:175], v[192:195], v[40:43], v[172:175]
	v_fma_f32 v222, v166, v179, -v180
	v_fma_f32 v223, v167, v179, -v180
	v_mfma_f32_16x16x32_bf16 v[168:171], v[196:199], v[12:15], v[168:171]
	v_exp_f32_e32 v220, v220
	v_exp_f32_e32 v221, v221
	v_mfma_f32_16x16x32_bf16 v[172:175], v[196:199], v[44:47], v[172:175]
	v_exp_f32_e32 v222, v222
	v_exp_f32_e32 v223, v223
	v_mfma_f32_16x16x32_bf16 v[168:171], v[200:203], v[16:19], v[168:171]
	v_add_f32_e32 v176, v176, v216
	v_add_f32_e32 v176, v176, v217
	v_mfma_f32_16x16x32_bf16 v[172:175], v[200:203], v[48:51], v[172:175]
	v_cvt_pk_bf16_f32 v88, v216, v217
	v_add_f32_e32 v176, v176, v218
	v_mfma_f32_16x16x32_bf16 v[168:171], v[204:207], v[20:23], v[168:171]
	v_add_f32_e32 v176, v176, v219
	v_cvt_pk_bf16_f32 v89, v218, v219
	v_mfma_f32_16x16x32_bf16 v[172:175], v[204:207], v[52:55], v[172:175]
	v_add_f32_e32 v177, v177, v220
	v_add_f32_e32 v177, v177, v221
	v_mfma_f32_16x16x32_bf16 v[168:171], v[208:211], v[24:27], v[168:171]
	v_cvt_pk_bf16_f32 v120, v220, v221
	v_add_f32_e32 v177, v177, v222
	v_mfma_f32_16x16x32_bf16 v[172:175], v[208:211], v[56:59], v[172:175]
	v_add_f32_e32 v177, v177, v223
	v_cvt_pk_bf16_f32 v121, v222, v223
	v_mfma_f32_16x16x32_bf16 v[168:171], v[212:215], v[28:31], v[168:171]
	v_mfma_f32_16x16x32_bf16 v[172:175], v[212:215], v[60:63], v[172:175]
	s_waitcnt lgkmcnt(0)
	ds_read_b128 v[184:187], v233 offset:8448
	ds_read_b128 v[188:191], v233 offset:8512
	ds_read_b128 v[192:195], v233 offset:8576
	ds_read_b128 v[196:199], v233 offset:8640
	ds_read_b128 v[200:203], v233 offset:8704
	ds_read_b128 v[204:207], v233 offset:8768
	ds_read_b128 v[208:211], v233 offset:8832
	ds_read_b128 v[212:215], v233 offset:8896
	v_mfma_f32_16x16x32_bf16 v[160:163], v[128:131], v[0:3], 0
	v_fma_f32 v216, v168, v178, -v180
	v_fma_f32 v217, v169, v178, -v180
	v_mfma_f32_16x16x32_bf16 v[164:167], v[128:131], v[32:35], 0
	v_fma_f32 v218, v170, v178, -v180
	v_fma_f32 v219, v171, v178, -v180
	v_mfma_f32_16x16x32_bf16 v[160:163], v[132:135], v[4:7], v[160:163]
	v_exp_f32_e32 v216, v216
	v_exp_f32_e32 v217, v217
	v_mfma_f32_16x16x32_bf16 v[164:167], v[132:135], v[36:39], v[164:167]
	v_exp_f32_e32 v218, v218
	v_exp_f32_e32 v219, v219
	v_mfma_f32_16x16x32_bf16 v[160:163], v[136:139], v[8:11], v[160:163]
	v_fma_f32 v220, v172, v179, -v180
	v_fma_f32 v221, v173, v179, -v180
	v_mfma_f32_16x16x32_bf16 v[164:167], v[136:139], v[40:43], v[164:167]
	v_fma_f32 v222, v174, v179, -v180
	v_fma_f32 v223, v175, v179, -v180
	v_mfma_f32_16x16x32_bf16 v[160:163], v[140:143], v[12:15], v[160:163]
	v_exp_f32_e32 v220, v220
	v_exp_f32_e32 v221, v221
	v_mfma_f32_16x16x32_bf16 v[164:167], v[140:143], v[44:47], v[164:167]
	v_exp_f32_e32 v222, v222
	v_exp_f32_e32 v223, v223
	v_mfma_f32_16x16x32_bf16 v[160:163], v[144:147], v[16:19], v[160:163]
	v_add_f32_e32 v176, v176, v216
	v_add_f32_e32 v176, v176, v217
	v_mfma_f32_16x16x32_bf16 v[164:167], v[144:147], v[48:51], v[164:167]
	v_cvt_pk_bf16_f32 v90, v216, v217
	v_add_f32_e32 v176, v176, v218
	v_mfma_f32_16x16x32_bf16 v[160:163], v[148:151], v[20:23], v[160:163]
	v_add_f32_e32 v176, v176, v219
	v_cvt_pk_bf16_f32 v91, v218, v219
	v_mfma_f32_16x16x32_bf16 v[164:167], v[148:151], v[52:55], v[164:167]
	v_add_f32_e32 v177, v177, v220
	v_add_f32_e32 v177, v177, v221
	v_mfma_f32_16x16x32_bf16 v[160:163], v[152:155], v[24:27], v[160:163]
	v_cvt_pk_bf16_f32 v122, v220, v221
	v_add_f32_e32 v177, v177, v222
	v_mfma_f32_16x16x32_bf16 v[164:167], v[152:155], v[56:59], v[164:167]
	v_add_f32_e32 v177, v177, v223
	v_cvt_pk_bf16_f32 v123, v222, v223
	v_mfma_f32_16x16x32_bf16 v[160:163], v[156:159], v[28:31], v[160:163]
	v_mfma_f32_16x16x32_bf16 v[164:167], v[156:159], v[60:63], v[164:167]
	s_waitcnt lgkmcnt(0)
	s_nop 6
	v_mfma_f32_16x16x32_bf16 v[168:171], v[184:187], v[0:3], 0
	v_fma_f32 v216, v160, v178, -v180
	v_fma_f32 v217, v161, v178, -v180
	v_mfma_f32_16x16x32_bf16 v[172:175], v[184:187], v[32:35], 0
	v_fma_f32 v218, v162, v178, -v180
	v_fma_f32 v219, v163, v178, -v180
	v_mfma_f32_16x16x32_bf16 v[168:171], v[188:191], v[4:7], v[168:171]
	v_exp_f32_e32 v216, v216
	v_exp_f32_e32 v217, v217
	v_mfma_f32_16x16x32_bf16 v[172:175], v[188:191], v[36:39], v[172:175]
	v_exp_f32_e32 v218, v218
	v_exp_f32_e32 v219, v219
	v_mfma_f32_16x16x32_bf16 v[168:171], v[192:195], v[8:11], v[168:171]
	v_fma_f32 v220, v164, v179, -v180
	v_fma_f32 v221, v165, v179, -v180
	v_mfma_f32_16x16x32_bf16 v[172:175], v[192:195], v[40:43], v[172:175]
	v_fma_f32 v222, v166, v179, -v180
	v_fma_f32 v223, v167, v179, -v180
	v_mfma_f32_16x16x32_bf16 v[168:171], v[196:199], v[12:15], v[168:171]
	v_exp_f32_e32 v220, v220
	v_exp_f32_e32 v221, v221
	v_mfma_f32_16x16x32_bf16 v[172:175], v[196:199], v[44:47], v[172:175]
	v_exp_f32_e32 v222, v222
	v_exp_f32_e32 v223, v223
	v_mfma_f32_16x16x32_bf16 v[168:171], v[200:203], v[16:19], v[168:171]
	v_add_f32_e32 v176, v176, v216
	v_add_f32_e32 v176, v176, v217
	v_mfma_f32_16x16x32_bf16 v[172:175], v[200:203], v[48:51], v[172:175]
	v_cvt_pk_bf16_f32 v92, v216, v217
	v_add_f32_e32 v176, v176, v218
	v_mfma_f32_16x16x32_bf16 v[168:171], v[204:207], v[20:23], v[168:171]
	v_add_f32_e32 v176, v176, v219
	v_cvt_pk_bf16_f32 v93, v218, v219
	v_mfma_f32_16x16x32_bf16 v[172:175], v[204:207], v[52:55], v[172:175]
	v_add_f32_e32 v177, v177, v220
	v_add_f32_e32 v177, v177, v221
	v_mfma_f32_16x16x32_bf16 v[168:171], v[208:211], v[24:27], v[168:171]
	v_cvt_pk_bf16_f32 v124, v220, v221
	v_add_f32_e32 v177, v177, v222
	v_mfma_f32_16x16x32_bf16 v[172:175], v[208:211], v[56:59], v[172:175]
	v_add_f32_e32 v177, v177, v223
	v_cvt_pk_bf16_f32 v125, v222, v223
	v_mfma_f32_16x16x32_bf16 v[168:171], v[212:215], v[28:31], v[168:171]
	v_mfma_f32_16x16x32_bf16 v[172:175], v[212:215], v[60:63], v[172:175]
	s_nop 7
	v_fma_f32 v216, v168, v178, -v180
	v_fma_f32 v217, v169, v178, -v180
	v_fma_f32 v218, v170, v178, -v180
	v_fma_f32 v219, v171, v178, -v180
	v_exp_f32_e32 v216, v216
	v_exp_f32_e32 v217, v217
	v_exp_f32_e32 v218, v218
	v_exp_f32_e32 v219, v219
	v_fma_f32 v220, v172, v179, -v180
	v_fma_f32 v221, v173, v179, -v180
	v_fma_f32 v222, v174, v179, -v180
	v_fma_f32 v223, v175, v179, -v180
	v_exp_f32_e32 v220, v220
	v_exp_f32_e32 v221, v221
	v_exp_f32_e32 v222, v222
	v_exp_f32_e32 v223, v223
	v_add_f32_e32 v176, v176, v216
	v_add_f32_e32 v176, v176, v217
	v_cvt_pk_bf16_f32 v94, v216, v217
	v_add_f32_e32 v176, v176, v218
	v_add_f32_e32 v176, v176, v219
	v_cvt_pk_bf16_f32 v95, v218, v219
	v_add_f32_e32 v177, v177, v220
	v_add_f32_e32 v177, v177, v221
	v_cvt_pk_bf16_f32 v126, v220, v221
	v_add_f32_e32 v177, v177, v222
	v_add_f32_e32 v177, v177, v223
	v_cvt_pk_bf16_f32 v127, v222, v223
	s_barrier
	global_load_dwordx4 v[128:131], v225, s[8:9]
	s_add_u32 s8, s8, 0x14000
	s_addc_u32 s9, s9, 0
	global_load_dwordx4 v[132:135], v225, s[8:9]
	s_add_u32 s8, s8, 0x14000
	s_addc_u32 s9, s9, 0
	global_load_dwordx4 v[136:139], v225, s[8:9]
	s_add_u32 s8, s8, 0x14000
	s_addc_u32 s9, s9, 0
	global_load_dwordx4 v[140:143], v225, s[8:9]
	s_add_u32 s8, s8, 0x14000
	s_addc_u32 s9, s9, 0
	global_load_dwordx4 v[144:147], v225, s[8:9]
	s_add_u32 s8, s8, 0x14000
	s_addc_u32 s9, s9, 0
	global_load_dwordx4 v[148:151], v225, s[8:9]
	s_add_u32 s8, s8, 0x14000
	s_addc_u32 s9, s9, 0
	global_load_dwordx4 v[152:155], v225, s[8:9]
	s_add_u32 s8, s8, 0x14000
	s_addc_u32 s9, s9, 0
	global_load_dwordx4 v[156:159], v225, s[8:9]
	s_add_u32 s8, s8, 0x14000
	s_addc_u32 s9, s9, 0
	global_load_dwordx4 v[184:187], v225, s[8:9]
	s_add_u32 s8, s8, 0x14000
	s_addc_u32 s9, s9, 0
	global_load_dwordx4 v[188:191], v225, s[8:9]
	s_add_u32 s8, s8, 0x14000
	s_addc_u32 s9, s9, 0
	global_load_dwordx4 v[192:195], v225, s[8:9]
	s_add_u32 s8, s8, 0x14000
	s_addc_u32 s9, s9, 0
	global_load_dwordx4 v[196:199], v225, s[8:9]
	s_add_u32 s8, s8, 0x14000
	s_addc_u32 s9, s9, 0
	global_load_dwordx4 v[200:203], v225, s[8:9]
	s_add_u32 s8, s8, 0x14000
	s_addc_u32 s9, s9, 0
	global_load_dwordx4 v[204:207], v225, s[8:9]
	s_add_u32 s8, s8, 0x14000
	s_addc_u32 s9, s9, 0
	global_load_dwordx4 v[208:211], v225, s[8:9]
	s_add_u32 s8, s8, 0x14000
	s_addc_u32 s9, s9, 0
	global_load_dwordx4 v[212:215], v225, s[8:9]
	s_add_i32 s16, s69, s86
	s_cmpk_lt_i32 s16, 0x300
	s_cselect_b32 s16, s16, s69
	s_and_b32 s0, s16, 31
	s_lshr_b32 s1, s16, 8
	s_lshl_b32 s1, s1, 5
	s_add_i32 s1, s1, s0
	s_mul_i32 s0, s1, 2731
	s_lshr_b32 s0, s0, 16
	s_mul_i32 s17, s0, 24
	s_sub_i32 s1, s1, s17
	s_bfe_u32 s17, s16, 0x30005
	s_mul_i32 s17, s17, 24
	s_add_i32 s1, s1, s17
	s_lshl_b32 s11, s1, 19
	s_lshl_b32 s12, s0, 9
	s_add_u32 s11, s11, s12
	s_add_u32 s12, s11, 0xf000000
	s_add_u32 s10, s4, s12
	s_addc_u32 s11, s5, 0
	s_lshl_b32 s12, s1, 12
	s_lshl_b32 s13, s0, 2
	s_add_u32 s12, s12, s13
	s_add_u32 s12, s12, 0x1fa60000
	s_add_u32 s12, s4, s12
	s_addc_u32 s13, s5, 0
	global_load_dwordx4 v[0:3], v228, s[10:11] offset:0
	global_load_dwordx4 v[4:7], v228, s[10:11] offset:64
	global_load_dwordx4 v[8:11], v228, s[10:11] offset:128
	global_load_dwordx4 v[12:15], v228, s[10:11] offset:192
	global_load_dwordx4 v[16:19], v228, s[10:11] offset:256
	global_load_dwordx4 v[20:23], v228, s[10:11] offset:320
	global_load_dwordx4 v[24:27], v228, s[10:11] offset:384
	global_load_dwordx4 v[28:31], v228, s[10:11] offset:448
	global_load_dwordx4 v[32:35], v229, s[10:11] offset:0
	global_load_dwordx4 v[36:39], v229, s[10:11] offset:64
	global_load_dwordx4 v[40:43], v229, s[10:11] offset:128
	global_load_dwordx4 v[44:47], v229, s[10:11] offset:192
	global_load_dwordx4 v[48:51], v229, s[10:11] offset:256
	global_load_dwordx4 v[52:55], v229, s[10:11] offset:320
	global_load_dwordx4 v[56:59], v229, s[10:11] offset:384
	global_load_dwordx4 v[60:63], v229, s[10:11] offset:448
	global_load_dword v247, v230, s[12:13]
	global_load_dword v248, v230, s[12:13] offset:2048
	ds_bpermute_b32 v242, v236, v176
	s_waitcnt lgkmcnt(0)
	v_add_f32_e32 v176, v176, v242
	ds_bpermute_b32 v242, v237, v176
	s_waitcnt lgkmcnt(0)
	v_add_f32_e32 v176, v176, v242
	ds_bpermute_b32 v242, v236, v177
	s_waitcnt lgkmcnt(0)
	v_add_f32_e32 v177, v177, v242
	ds_bpermute_b32 v242, v237, v177
	s_waitcnt lgkmcnt(0)
	v_add_f32_e32 v177, v177, v242
	v_rcp_f32_e32 v240, v176
	v_rcp_f32_e32 v241, v177
	s_waitcnt vmcnt(30)
	ds_write_b128 v250, v[128:131] offset:0
	ds_write_b128 v250, v[132:135] offset:4224
	ds_write_b128 v250, v[136:139] offset:16896
	ds_write_b128 v250, v[140:143] offset:21120
	s_waitcnt vmcnt(26)
	ds_write_b128 v250, v[144:147] offset:33792
	ds_write_b128 v250, v[148:151] offset:38016
	ds_write_b128 v250, v[152:155] offset:50688
	ds_write_b128 v250, v[156:159] offset:54912
	s_waitcnt vmcnt(22)
	ds_write_b128 v251, v[184:187] offset:0
	ds_write_b128 v251, v[188:191] offset:4224
	ds_write_b128 v251, v[192:195] offset:16896
	ds_write_b128 v251, v[196:199] offset:21120
	s_waitcnt vmcnt(18)
	ds_write_b128 v251, v[200:203] offset:33792
	ds_write_b128 v251, v[204:207] offset:38016
	ds_write_b128 v251, v[208:211] offset:50688
	ds_write_b128 v251, v[212:215] offset:54912
	s_waitcnt lgkmcnt(0)
	s_barrier
	s_and_b32 s0, s16, 31
	s_lshr_b32 s1, s16, 8
	s_lshl_b32 s1, s1, 5
	s_add_i32 s1, s1, s0
	s_mul_i32 s0, s1, 2731
	s_lshr_b32 s0, s0, 16
	s_mul_i32 s17, s0, 24
	s_sub_i32 s1, s1, s17
	s_bfe_u32 s17, s16, 0x30005
	s_mul_i32 s17, s17, 24
	s_add_i32 s1, s1, s17
	s_lshr_b32 s10, s1, 5
	s_sub_i32 s11, s1, 64
	s_lshr_b32 s11, s11, 4
	s_add_i32 s11, s11, 2
	s_cmp_lt_u32 s1, 64
	s_cselect_b32 s10, s10, s11
	s_lshl_b32 s11, s10, 19
	s_lshl_b32 s12, s0, 9
	s_add_u32 s11, s11, s12
	s_add_u32 s11, s11, 0x15040000
	s_add_u32 s6, s4, s11
	s_addc_u32 s7, s5, 0
	global_load_dwordx4 v[184:187], v224, s[6:7]
	s_add_u32 s6, s6, 0x8000
	s_addc_u32 s7, s7, 0
	global_load_dwordx4 v[188:191], v224, s[6:7]
	s_add_u32 s6, s6, 0x8000
	s_addc_u32 s7, s7, 0
	global_load_dwordx4 v[192:195], v224, s[6:7]
	s_add_u32 s6, s6, 0x8000
	s_addc_u32 s7, s7, 0
	global_load_dwordx4 v[196:199], v224, s[6:7]
	s_add_u32 s6, s6, 0x8000
	s_addc_u32 s7, s7, 0
	global_load_dwordx4 v[200:203], v224, s[6:7]
	s_add_u32 s6, s6, 0x8000
	s_addc_u32 s7, s7, 0
	global_load_dwordx4 v[204:207], v224, s[6:7]
	s_add_u32 s6, s6, 0x8000
	s_addc_u32 s7, s7, 0
	global_load_dwordx4 v[208:211], v224, s[6:7]
	s_add_u32 s6, s6, 0x8000
	s_addc_u32 s7, s7, 0
	global_load_dwordx4 v[212:215], v224, s[6:7]
	s_mov_b32 s18, 0
	v_mov_b32_e32 v234, v232
	v_add_u32_e32 v235, 16896, v232
	ds_read_b64 v[128:129], v234 offset:0
	ds_read_b64 v[130:131], v234 offset:32
	ds_read_b64 v[132:133], v234 offset:64
	ds_read_b64 v[134:135], v234 offset:96
	ds_read_b64 v[136:137], v234 offset:128
	ds_read_b64 v[138:139], v234 offset:160
	ds_read_b64 v[140:141], v234 offset:192
	ds_read_b64 v[142:143], v234 offset:224
	ds_read_b64 v[144:145], v234 offset:256
	ds_read_b64 v[146:147], v234 offset:288
	ds_read_b64 v[148:149], v234 offset:320
	ds_read_b64 v[150:151], v234 offset:352
